# JIT code warm: in the last K-loop iteration of every tile each wave loads 1KB (LDS-DMA to a scratch slot) of the 8KB of program text around the epilogue / peeled pair into L2
# speedup vs baseline: 1.0029x; 1.0029x over previous
; template <class Epi, class Sched, bool ALIGN_EPI = false, bool SP2 = false>
; __device__ __forceinline__ void gemm_phase(PG8_LAS unsigned char* lds, const Gemm g, const Sched& S, const Epi& E, int wave_s) {
;     ...
;         for (int t = peeled ? 2 : 0; t < nt; t += 2) {
;             const bool last = (t == nt - 2);
;             const char* a1 = cA + (size_t)(t + 1) * kstep;
;             const char* a2 = last ? nA : cA + (size_t)(t + 2) * kstep; const char* b2 = last ? nB : cB + (size_t)(t + 2) * kstep;
;             const char* a3 = a2 + kstep; const char* b3 = b2 + kstep;
;             if (last && has_next) S.a_ready(nxt);
.LBB0_107:
	s_cmp_eq_u32 s76, 12
	s_cbranch_scc1 .Lcw_0

; template <class Epi, class Sched, bool ALIGN_EPI = false, bool SP2 = false>
; __device__ __forceinline__ void gemm_phase(PG8_LAS unsigned char* lds, const Gemm g, const Sched& S, const Epi& E, int wave_s) {
;     ...
;         for (int t = peeled ? 2 : 0; t < nt; t += 2) {
;             const bool last = (t == nt - 2);
;             const char* a1 = cA + (size_t)(t + 1) * kstep;
;             const char* a2 = last ? nA : cA + (size_t)(t + 2) * kstep; const char* b2 = last ? nB : cB + (size_t)(t + 2) * kstep;
;             const char* a3 = a2 + kstep; const char* b3 = b2 + kstep;
;             if (last && has_next) S.a_ready(nxt);
.Lcw_0:
	v_mbcnt_lo_u32_b32 v152, -1, 0
	v_mbcnt_hi_u32_b32 v152, -1, v152
	v_lshlrev_b32_e32 v152, 4, v152
	s_getpc_b64 s[98:99]
.Lcwp_0:
	s_sub_u32 s98, s98, .Lcwp_0-.LBB0_107+3072
	s_subb_u32 s99, s99, 0
	s_lshr_b32 s100, s33, 3
	s_and_b32 s100, s100, 7
	s_lshl_b32 s100, s100, 10
	s_add_u32 s98, s98, s100
	s_addc_u32 s99, s99, 0
	s_mov_b32 m0, 0x23400
	s_nop 0
	global_load_lds_dwordx4 v152, s[98:99]
	s_branch .Lcwb_0

; template <class Epi, class Sched, bool ALIGN_EPI = false, bool SP2 = false>
; __device__ __forceinline__ void gemm_phase(PG8_LAS unsigned char* lds, const Gemm g, const Sched& S, const Epi& E, int wave_s) {
;     ...
;         for (int t = peeled ? 2 : 0; t < nt; t += 2) {
;             const bool last = (t == nt - 2);
;             const char* a1 = cA + (size_t)(t + 1) * kstep;
;             const char* a2 = last ? nA : cA + (size_t)(t + 2) * kstep; const char* b2 = last ? nB : cB + (size_t)(t + 2) * kstep;
;             const char* a3 = a2 + kstep; const char* b3 = b2 + kstep;
;             if (last && has_next) S.a_ready(nxt);
.LBB0_329:
	s_cmp_eq_u32 s82, 40
	s_cbranch_scc1 .Lcw_1

; template <class Epi, class Sched, bool ALIGN_EPI = false, bool SP2 = false>
; __device__ __forceinline__ void gemm_phase(PG8_LAS unsigned char* lds, const Gemm g, const Sched& S, const Epi& E, int wave_s) {
;     ...
;         for (int t = peeled ? 2 : 0; t < nt; t += 2) {
;             const bool last = (t == nt - 2);
;             const char* a1 = cA + (size_t)(t + 1) * kstep;
;             const char* a2 = last ? nA : cA + (size_t)(t + 2) * kstep; const char* b2 = last ? nB : cB + (size_t)(t + 2) * kstep;
;             const char* a3 = a2 + kstep; const char* b3 = b2 + kstep;
;             if (last && has_next) S.a_ready(nxt);
.Lcw_1:
	v_mbcnt_lo_u32_b32 v140, -1, 0
	v_mbcnt_hi_u32_b32 v140, -1, v140
	v_lshlrev_b32_e32 v140, 4, v140
	s_getpc_b64 s[98:99]
.Lcwp_1:
	s_sub_u32 s98, s98, .Lcwp_1-.LBB0_329
	s_subb_u32 s99, s99, 0
	s_lshr_b32 s100, s33, 3
	s_and_b32 s100, s100, 7
	s_lshl_b32 s100, s100, 10
	s_add_u32 s98, s98, s100
	s_addc_u32 s99, s99, 0
	s_mov_b32 m0, 0x23400
	s_nop 0
	global_load_lds_dwordx4 v140, s[98:99]
	s_branch .Lcwb_1

; template <class Epi, class Sched, bool ALIGN_EPI = false, bool SP2 = false>
; __device__ __forceinline__ void gemm_phase(PG8_LAS unsigned char* lds, const Gemm g, const Sched& S, const Epi& E, int wave_s) {
;     ...
;         for (int t = peeled ? 2 : 0; t < nt; t += 2) {
;             const bool last = (t == nt - 2);
;             const char* a1 = cA + (size_t)(t + 1) * kstep;
;             const char* a2 = last ? nA : cA + (size_t)(t + 2) * kstep; const char* b2 = last ? nB : cB + (size_t)(t + 2) * kstep;
;             const char* a3 = a2 + kstep; const char* b3 = b2 + kstep;
;             if (last && has_next) S.a_ready(nxt);
.LBB0_419:
	s_cmp_eq_u32 s96, 12
	s_cbranch_scc1 .Lcw_2

; template <class Epi, class Sched, bool ALIGN_EPI = false, bool SP2 = false>
; __device__ __forceinline__ void gemm_phase(PG8_LAS unsigned char* lds, const Gemm g, const Sched& S, const Epi& E, int wave_s) {
;     ...
;         for (int t = peeled ? 2 : 0; t < nt; t += 2) {
;             const bool last = (t == nt - 2);
;             const char* a1 = cA + (size_t)(t + 1) * kstep;
;             const char* a2 = last ? nA : cA + (size_t)(t + 2) * kstep; const char* b2 = last ? nB : cB + (size_t)(t + 2) * kstep;
;             const char* a3 = a2 + kstep; const char* b3 = b2 + kstep;
;             if (last && has_next) S.a_ready(nxt);
.LBB0_822:
	s_cmp_eq_u32 vcc_lo, 12
	s_cbranch_scc1 .Lcw_3

; template <class Epi, class Sched, bool ALIGN_EPI = false, bool SP2 = false>
; __device__ __forceinline__ void gemm_phase(PG8_LAS unsigned char* lds, const Gemm g, const Sched& S, const Epi& E, int wave_s) {
;     ...
;         for (int t = peeled ? 2 : 0; t < nt; t += 2) {
;             const bool last = (t == nt - 2);
;             const char* a1 = cA + (size_t)(t + 1) * kstep;
;             const char* a2 = last ? nA : cA + (size_t)(t + 2) * kstep; const char* b2 = last ? nB : cB + (size_t)(t + 2) * kstep;
;             const char* a3 = a2 + kstep; const char* b3 = b2 + kstep;
;             if (last && has_next) S.a_ready(nxt);
.LBB0_912:
	s_cmp_eq_u32 s95, 12
	s_cbranch_scc1 .Lcw_4

; template <class Epi, class Sched, bool ALIGN_EPI = false, bool SP2 = false>
; __device__ __forceinline__ void gemm_phase(PG8_LAS unsigned char* lds, const Gemm g, const Sched& S, const Epi& E, int wave_s) {
;     ...
;         for (int t = peeled ? 2 : 0; t < nt; t += 2) {
;             const bool last = (t == nt - 2);
;             const char* a1 = cA + (size_t)(t + 1) * kstep;
;             const char* a2 = last ? nA : cA + (size_t)(t + 2) * kstep; const char* b2 = last ? nB : cB + (size_t)(t + 2) * kstep;
;             const char* a3 = a2 + kstep; const char* b3 = b2 + kstep;
;             if (last && has_next) S.a_ready(nxt);
.LBB0_1188:
	s_cmp_eq_u32 vcc_lo, 40
	s_cbranch_scc1 .Lcw_5

; template <class Epi, class Sched, bool ALIGN_EPI = false, bool SP2 = false>
; __device__ __forceinline__ void gemm_phase(PG8_LAS unsigned char* lds, const Gemm g, const Sched& S, const Epi& E, int wave_s) {
;     ...
;         for (int t = peeled ? 2 : 0; t < nt; t += 2) {
;             const bool last = (t == nt - 2);
;             const char* a1 = cA + (size_t)(t + 1) * kstep;
;             const char* a2 = last ? nA : cA + (size_t)(t + 2) * kstep; const char* b2 = last ? nB : cB + (size_t)(t + 2) * kstep;
;             const char* a3 = a2 + kstep; const char* b3 = b2 + kstep;
;             if (last && has_next) S.a_ready(nxt);
.LBB0_1278:
	s_cmp_eq_u32 vcc_hi, 12
	s_cbranch_scc1 .Lcw_6

; template <class Epi, class Sched, bool ALIGN_EPI = false, bool SP2 = false>
; __device__ __forceinline__ void gemm_phase(PG8_LAS unsigned char* lds, const Gemm g, const Sched& S, const Epi& E, int wave_s) {
;     ...
;         for (int t = peeled ? 2 : 0; t < nt; t += 2) {
;             const bool last = (t == nt - 2);
;             const char* a1 = cA + (size_t)(t + 1) * kstep;
;             const char* a2 = last ? nA : cA + (size_t)(t + 2) * kstep; const char* b2 = last ? nB : cB + (size_t)(t + 2) * kstep;
;             const char* a3 = a2 + kstep; const char* b3 = b2 + kstep;
;             if (last && has_next) S.a_ready(nxt);
.LBB0_1666:
	s_cmp_eq_u32 s77, 40
	s_cbranch_scc1 .Lcw_7

; template <class Epi, class Sched, bool ALIGN_EPI = false, bool SP2 = false>
; __device__ __forceinline__ void gemm_phase(PG8_LAS unsigned char* lds, const Gemm g, const Sched& S, const Epi& E, int wave_s) {
;     ...
;         for (int t = peeled ? 2 : 0; t < nt; t += 2) {
;             const bool last = (t == nt - 2);
;             const char* a1 = cA + (size_t)(t + 1) * kstep;
;             const char* a2 = last ? nA : cA + (size_t)(t + 2) * kstep; const char* b2 = last ? nB : cB + (size_t)(t + 2) * kstep;
;             const char* a3 = a2 + kstep; const char* b3 = b2 + kstep;
;             if (last && has_next) S.a_ready(nxt);
.LBB0_1764:
	s_cmp_eq_u32 s88, 12
	s_cbranch_scc1 .Lcw_8

; template <class Epi, class Sched, bool ALIGN_EPI = false, bool SP2 = false>
; __device__ __forceinline__ void gemm_phase(PG8_LAS unsigned char* lds, const Gemm g, const Sched& S, const Epi& E, int wave_s) {
;     ...
;         for (int t = peeled ? 2 : 0; t < nt; t += 2) {
;             const bool last = (t == nt - 2);
;             const char* a1 = cA + (size_t)(t + 1) * kstep;
;             const char* a2 = last ? nA : cA + (size_t)(t + 2) * kstep; const char* b2 = last ? nB : cB + (size_t)(t + 2) * kstep;
;             const char* a3 = a2 + kstep; const char* b3 = b2 + kstep;
;             if (last && has_next) S.a_ready(nxt);
.LBB0_2302:
	s_cmp_eq_u32 s79, 12
	s_cbranch_scc1 .Lcw_9

; template <class Epi, class Sched, bool ALIGN_EPI = false, bool SP2 = false>
; __device__ __forceinline__ void gemm_phase(PG8_LAS unsigned char* lds, const Gemm g, const Sched& S, const Epi& E, int wave_s) {
;     ...
;         for (int t = peeled ? 2 : 0; t < nt; t += 2) {
;             const bool last = (t == nt - 2);
;             const char* a1 = cA + (size_t)(t + 1) * kstep;
;             const char* a2 = last ? nA : cA + (size_t)(t + 2) * kstep; const char* b2 = last ? nB : cB + (size_t)(t + 2) * kstep;
;             const char* a3 = a2 + kstep; const char* b3 = b2 + kstep;
;             if (last && has_next) S.a_ready(nxt);
.LBB0_2390:
	s_cmp_eq_u32 s70, 12
	s_cbranch_scc1 .Lcw_10

; template <class Epi, class Sched, bool ALIGN_EPI = false, bool SP2 = false>
; __device__ __forceinline__ void gemm_phase(PG8_LAS unsigned char* lds, const Gemm g, const Sched& S, const Epi& E, int wave_s) {
;     ...
;         for (int t = peeled ? 2 : 0; t < nt; t += 2) {
;             const bool last = (t == nt - 2);
;             const char* a1 = cA + (size_t)(t + 1) * kstep;
;             const char* a2 = last ? nA : cA + (size_t)(t + 2) * kstep; const char* b2 = last ? nB : cB + (size_t)(t + 2) * kstep;
;             const char* a3 = a2 + kstep; const char* b3 = b2 + kstep;
;             if (last && has_next) S.a_ready(nxt);
.LBB0_2472:
	s_cmp_eq_u32 s56, 40
	s_cbranch_scc1 .Lcw_11
